# HG scan: q.S output dot split into two independent packed accumulation chains (ILP test, +1 op per token)
# baseline (speedup 1.0000x reference)
.LBB0_219:
	v_lshl_add_u32 v188, s25, 9, v69
	v_lshl_add_u32 v189, s25, 7, v72
	v_add_u32_e32 v190, 0x8400, v189
	v_add_u32_e32 v189, 0x8000, v189
	ds_read2_b32 v[172:173], v189 offset1:32
	ds_read2_b32 v[174:175], v189 offset0:64 offset1:96
	ds_read2_b32 v[176:177], v189 offset0:128 offset1:160
	ds_read2_b32 v[178:179], v189 offset0:192 offset1:224
	ds_read_b128 v[120:123], v188 offset:16384
	ds_read_b128 v[124:127], v188 offset:16640
	ds_read_b128 v[112:115], v188 offset:0
	ds_read_b128 v[116:119], v188 offset:256
	ds_read_b128 v[136:139], v188 offset:16896
	ds_read_b128 v[144:147], v188 offset:17152
	ds_read_b128 v[156:159], v188 offset:17408
	ds_read_b128 v[168:171], v188 offset:17664
	ds_read_b128 v[128:131], v188 offset:512
	ds_read_b128 v[132:135], v188 offset:768
	s_waitcnt lgkmcnt(8)
	v_pk_add_f32 v[230:231], v[172:173], v[36:37] op_sel_hi:[0,1] neg_lo:[0,1] neg_hi:[0,1]
	v_pk_add_f32 v[232:233], v[172:173], v[48:49] op_sel_hi:[0,1] neg_lo:[0,1] neg_hi:[0,1]
	v_pk_add_f32 v[234:235], v[172:173], v[38:39] op_sel_hi:[0,1] neg_lo:[0,1] neg_hi:[0,1]
	v_pk_add_f32 v[236:237], v[172:173], v[32:33] op_sel_hi:[0,1] neg_lo:[0,1] neg_hi:[0,1]
	v_pk_fma_f32 v[244:245], v[120:121], v[230:231], v[36:37]
	v_pk_fma_f32 v[246:247], v[122:123], v[232:233], v[48:49]
	v_pk_fma_f32 v[248:249], v[124:125], v[234:235], v[38:39]
	v_pk_fma_f32 v[250:251], v[126:127], v[236:237], v[32:33]
	ds_read_b128 v[120:123], v188 offset:17920
	ds_read_b128 v[124:127], v188 offset:18176
	ds_read_b128 v[148:151], v188 offset:1024
	ds_read_b128 v[152:155], v188 offset:1280
	s_waitcnt lgkmcnt(8)
	v_pk_add_f32 v[230:231], v[172:173], v[244:245] op_sel:[1,0] op_sel_hi:[1,1] neg_lo:[0,1] neg_hi:[0,1]
	v_pk_add_f32 v[232:233], v[172:173], v[246:247] op_sel:[1,0] op_sel_hi:[1,1] neg_lo:[0,1] neg_hi:[0,1]
	v_pk_add_f32 v[234:235], v[172:173], v[248:249] op_sel:[1,0] op_sel_hi:[1,1] neg_lo:[0,1] neg_hi:[0,1]
	v_pk_add_f32 v[236:237], v[172:173], v[250:251] op_sel:[1,0] op_sel_hi:[1,1] neg_lo:[0,1] neg_hi:[0,1]
	v_pk_fma_f32 v[36:37], v[136:137], v[230:231], v[244:245]
	v_pk_mul_f32 v[238:239], v[112:113], v[244:245]
	v_pk_fma_f32 v[48:49], v[138:139], v[232:233], v[246:247]
	v_pk_mul_f32 v[242:243], v[114:115], v[246:247]
	v_pk_fma_f32 v[38:39], v[144:145], v[234:235], v[248:249]
	v_pk_fma_f32 v[238:239], v[116:117], v[248:249], v[238:239]
	v_pk_fma_f32 v[32:33], v[146:147], v[236:237], v[250:251]
	v_pk_fma_f32 v[242:243], v[118:119], v[250:251], v[242:243]
	ds_read_b128 v[136:139], v188 offset:18432
	ds_read_b128 v[144:147], v188 offset:18688
	ds_read_b128 v[112:115], v188 offset:1536
	ds_read_b128 v[116:119], v188 offset:1792
	s_waitcnt lgkmcnt(8)
	v_pk_add_f32 v[230:231], v[174:175], v[36:37] op_sel_hi:[0,1] neg_lo:[0,1] neg_hi:[0,1]
	v_pk_add_f32 v[232:233], v[174:175], v[48:49] op_sel_hi:[0,1] neg_lo:[0,1] neg_hi:[0,1]
	v_pk_add_f32 v[234:235], v[174:175], v[38:39] op_sel_hi:[0,1] neg_lo:[0,1] neg_hi:[0,1]
	v_pk_add_f32 v[236:237], v[174:175], v[32:33] op_sel_hi:[0,1] neg_lo:[0,1] neg_hi:[0,1]
	v_pk_add_f32 v[238:239], v[238:239], v[242:243]
	v_add_f32_e32 v214, v238, v239
	v_pk_fma_f32 v[244:245], v[156:157], v[230:231], v[36:37]
	v_pk_mul_f32 v[240:241], v[128:129], v[36:37]
	v_pk_fma_f32 v[246:247], v[158:159], v[232:233], v[48:49]
	v_pk_mul_f32 v[196:197], v[130:131], v[48:49]
	v_pk_fma_f32 v[248:249], v[168:169], v[234:235], v[38:39]
	v_pk_fma_f32 v[240:241], v[132:133], v[38:39], v[240:241]
	v_pk_fma_f32 v[250:251], v[170:171], v[236:237], v[32:33]
	v_pk_fma_f32 v[196:197], v[134:135], v[32:33], v[196:197]
	ds_read_b128 v[156:159], v188 offset:18944
	ds_read_b128 v[168:171], v188 offset:19200
	ds_read_b128 v[128:131], v188 offset:2048
	ds_read_b128 v[132:135], v188 offset:2304
	s_waitcnt lgkmcnt(8)
	v_pk_add_f32 v[230:231], v[174:175], v[244:245] op_sel:[1,0] op_sel_hi:[1,1] neg_lo:[0,1] neg_hi:[0,1]
	v_pk_add_f32 v[232:233], v[174:175], v[246:247] op_sel:[1,0] op_sel_hi:[1,1] neg_lo:[0,1] neg_hi:[0,1]
	v_pk_add_f32 v[234:235], v[174:175], v[248:249] op_sel:[1,0] op_sel_hi:[1,1] neg_lo:[0,1] neg_hi:[0,1]
	v_pk_add_f32 v[236:237], v[174:175], v[250:251] op_sel:[1,0] op_sel_hi:[1,1] neg_lo:[0,1] neg_hi:[0,1]
	v_pk_add_f32 v[240:241], v[240:241], v[196:197]
	v_add_f32_e32 v215, v240, v241
	v_pk_fma_f32 v[36:37], v[120:121], v[230:231], v[244:245]
	v_pk_mul_f32 v[238:239], v[148:149], v[244:245]
	v_pk_fma_f32 v[48:49], v[122:123], v[232:233], v[246:247]
	v_pk_mul_f32 v[242:243], v[150:151], v[246:247]
	v_pk_fma_f32 v[38:39], v[124:125], v[234:235], v[248:249]
	v_pk_fma_f32 v[238:239], v[152:153], v[248:249], v[238:239]
	v_pk_fma_f32 v[32:33], v[126:127], v[236:237], v[250:251]
	v_pk_fma_f32 v[242:243], v[154:155], v[250:251], v[242:243]
	ds_read_b128 v[120:123], v188 offset:19456
	ds_read_b128 v[124:127], v188 offset:19712
	ds_read_b128 v[148:151], v188 offset:2560
	ds_read_b128 v[152:155], v188 offset:2816
	ds_read2_b32 v[180:181], v190 offset1:32
	ds_read2_b32 v[182:183], v190 offset0:64 offset1:96
	ds_read2_b32 v[184:185], v190 offset0:128 offset1:160
	ds_read2_b32 v[186:187], v190 offset0:192 offset1:224
	s_waitcnt lgkmcnt(12)
	v_pk_add_f32 v[230:231], v[176:177], v[36:37] op_sel_hi:[0,1] neg_lo:[0,1] neg_hi:[0,1]
	v_pk_add_f32 v[232:233], v[176:177], v[48:49] op_sel_hi:[0,1] neg_lo:[0,1] neg_hi:[0,1]
	v_pk_add_f32 v[234:235], v[176:177], v[38:39] op_sel_hi:[0,1] neg_lo:[0,1] neg_hi:[0,1]
	v_pk_add_f32 v[236:237], v[176:177], v[32:33] op_sel_hi:[0,1] neg_lo:[0,1] neg_hi:[0,1]
	v_pk_add_f32 v[238:239], v[238:239], v[242:243]
	v_add_f32_e32 v216, v238, v239
	v_pk_fma_f32 v[244:245], v[136:137], v[230:231], v[36:37]
	v_pk_mul_f32 v[240:241], v[112:113], v[36:37]
	v_pk_fma_f32 v[246:247], v[138:139], v[232:233], v[48:49]
	v_pk_mul_f32 v[196:197], v[114:115], v[48:49]
	v_pk_fma_f32 v[248:249], v[144:145], v[234:235], v[38:39]
	v_pk_fma_f32 v[240:241], v[116:117], v[38:39], v[240:241]
	v_pk_fma_f32 v[250:251], v[146:147], v[236:237], v[32:33]
	v_pk_fma_f32 v[196:197], v[118:119], v[32:33], v[196:197]
	ds_read_b128 v[136:139], v188 offset:19968
	ds_read_b128 v[144:147], v188 offset:20224
	ds_read_b128 v[112:115], v188 offset:3072
	ds_read_b128 v[116:119], v188 offset:3328
	s_waitcnt lgkmcnt(12)
	v_pk_add_f32 v[230:231], v[176:177], v[244:245] op_sel:[1,0] op_sel_hi:[1,1] neg_lo:[0,1] neg_hi:[0,1]
	v_pk_add_f32 v[232:233], v[176:177], v[246:247] op_sel:[1,0] op_sel_hi:[1,1] neg_lo:[0,1] neg_hi:[0,1]
	v_pk_add_f32 v[234:235], v[176:177], v[248:249] op_sel:[1,0] op_sel_hi:[1,1] neg_lo:[0,1] neg_hi:[0,1]
	v_pk_add_f32 v[236:237], v[176:177], v[250:251] op_sel:[1,0] op_sel_hi:[1,1] neg_lo:[0,1] neg_hi:[0,1]
	v_pk_add_f32 v[240:241], v[240:241], v[196:197]
	v_add_f32_e32 v217, v240, v241
	v_pk_fma_f32 v[36:37], v[156:157], v[230:231], v[244:245]
	v_pk_mul_f32 v[238:239], v[128:129], v[244:245]
	v_pk_fma_f32 v[48:49], v[158:159], v[232:233], v[246:247]
	v_pk_mul_f32 v[242:243], v[130:131], v[246:247]
	v_pk_fma_f32 v[38:39], v[168:169], v[234:235], v[248:249]
	v_pk_fma_f32 v[238:239], v[132:133], v[248:249], v[238:239]
	v_pk_fma_f32 v[32:33], v[170:171], v[236:237], v[250:251]
	v_pk_fma_f32 v[242:243], v[134:135], v[250:251], v[242:243]
	ds_read_b128 v[156:159], v188 offset:20480
	ds_read_b128 v[168:171], v188 offset:20736
	ds_read_b128 v[128:131], v188 offset:3584
	ds_read_b128 v[132:135], v188 offset:3840
	s_waitcnt lgkmcnt(12)
	v_pk_add_f32 v[230:231], v[178:179], v[36:37] op_sel_hi:[0,1] neg_lo:[0,1] neg_hi:[0,1]
	v_pk_add_f32 v[232:233], v[178:179], v[48:49] op_sel_hi:[0,1] neg_lo:[0,1] neg_hi:[0,1]
	v_pk_add_f32 v[234:235], v[178:179], v[38:39] op_sel_hi:[0,1] neg_lo:[0,1] neg_hi:[0,1]
	v_pk_add_f32 v[236:237], v[178:179], v[32:33] op_sel_hi:[0,1] neg_lo:[0,1] neg_hi:[0,1]
	v_pk_add_f32 v[238:239], v[238:239], v[242:243]
	v_add_f32_e32 v218, v238, v239
	v_pk_fma_f32 v[244:245], v[120:121], v[230:231], v[36:37]
	v_pk_mul_f32 v[240:241], v[148:149], v[36:37]
	v_pk_fma_f32 v[246:247], v[122:123], v[232:233], v[48:49]
	v_pk_mul_f32 v[196:197], v[150:151], v[48:49]
	v_pk_fma_f32 v[248:249], v[124:125], v[234:235], v[38:39]
	v_pk_fma_f32 v[240:241], v[152:153], v[38:39], v[240:241]
	v_pk_fma_f32 v[250:251], v[126:127], v[236:237], v[32:33]
	v_pk_fma_f32 v[196:197], v[154:155], v[32:33], v[196:197]
	ds_read_b128 v[120:123], v188 offset:20992
	ds_read_b128 v[124:127], v188 offset:21248
	ds_read_b128 v[148:151], v188 offset:4096
	ds_read_b128 v[152:155], v188 offset:4352
	s_waitcnt lgkmcnt(8)
	v_pk_add_f32 v[230:231], v[178:179], v[244:245] op_sel:[1,0] op_sel_hi:[1,1] neg_lo:[0,1] neg_hi:[0,1]
	v_pk_add_f32 v[232:233], v[178:179], v[246:247] op_sel:[1,0] op_sel_hi:[1,1] neg_lo:[0,1] neg_hi:[0,1]
	v_pk_add_f32 v[234:235], v[178:179], v[248:249] op_sel:[1,0] op_sel_hi:[1,1] neg_lo:[0,1] neg_hi:[0,1]
	v_pk_add_f32 v[236:237], v[178:179], v[250:251] op_sel:[1,0] op_sel_hi:[1,1] neg_lo:[0,1] neg_hi:[0,1]
	v_pk_add_f32 v[240:241], v[240:241], v[196:197]
	v_add_f32_e32 v219, v240, v241
	v_pk_fma_f32 v[36:37], v[136:137], v[230:231], v[244:245]
	v_pk_mul_f32 v[238:239], v[112:113], v[244:245]
	v_pk_fma_f32 v[48:49], v[138:139], v[232:233], v[246:247]
	v_pk_mul_f32 v[242:243], v[114:115], v[246:247]
	v_pk_fma_f32 v[38:39], v[144:145], v[234:235], v[248:249]
	v_pk_fma_f32 v[238:239], v[116:117], v[248:249], v[238:239]
	v_pk_fma_f32 v[32:33], v[146:147], v[236:237], v[250:251]
	v_pk_fma_f32 v[242:243], v[118:119], v[250:251], v[242:243]
	ds_read_b128 v[136:139], v188 offset:21504
	ds_read_b128 v[144:147], v188 offset:21760
	ds_read_b128 v[112:115], v188 offset:4608
	ds_read_b128 v[116:119], v188 offset:4864
	s_waitcnt lgkmcnt(8)
	v_pk_add_f32 v[230:231], v[180:181], v[36:37] op_sel_hi:[0,1] neg_lo:[0,1] neg_hi:[0,1]
	v_pk_add_f32 v[232:233], v[180:181], v[48:49] op_sel_hi:[0,1] neg_lo:[0,1] neg_hi:[0,1]
	v_pk_add_f32 v[234:235], v[180:181], v[38:39] op_sel_hi:[0,1] neg_lo:[0,1] neg_hi:[0,1]
	v_pk_add_f32 v[236:237], v[180:181], v[32:33] op_sel_hi:[0,1] neg_lo:[0,1] neg_hi:[0,1]
	v_pk_add_f32 v[238:239], v[238:239], v[242:243]
	v_add_f32_e32 v220, v238, v239
	v_pk_fma_f32 v[244:245], v[156:157], v[230:231], v[36:37]
	v_pk_mul_f32 v[240:241], v[128:129], v[36:37]
	v_pk_fma_f32 v[246:247], v[158:159], v[232:233], v[48:49]
	v_pk_mul_f32 v[196:197], v[130:131], v[48:49]
	v_pk_fma_f32 v[248:249], v[168:169], v[234:235], v[38:39]
	v_pk_fma_f32 v[240:241], v[132:133], v[38:39], v[240:241]
	v_pk_fma_f32 v[250:251], v[170:171], v[236:237], v[32:33]
	v_pk_fma_f32 v[196:197], v[134:135], v[32:33], v[196:197]
	ds_read_b128 v[156:159], v188 offset:22016
	ds_read_b128 v[168:171], v188 offset:22272
	ds_read_b128 v[128:131], v188 offset:5120
	ds_read_b128 v[132:135], v188 offset:5376
	s_waitcnt lgkmcnt(8)
	v_pk_add_f32 v[230:231], v[180:181], v[244:245] op_sel:[1,0] op_sel_hi:[1,1] neg_lo:[0,1] neg_hi:[0,1]
	v_pk_add_f32 v[232:233], v[180:181], v[246:247] op_sel:[1,0] op_sel_hi:[1,1] neg_lo:[0,1] neg_hi:[0,1]
	v_pk_add_f32 v[234:235], v[180:181], v[248:249] op_sel:[1,0] op_sel_hi:[1,1] neg_lo:[0,1] neg_hi:[0,1]
	v_pk_add_f32 v[236:237], v[180:181], v[250:251] op_sel:[1,0] op_sel_hi:[1,1] neg_lo:[0,1] neg_hi:[0,1]
	v_pk_add_f32 v[240:241], v[240:241], v[196:197]
	v_add_f32_e32 v221, v240, v241
	v_pk_fma_f32 v[36:37], v[120:121], v[230:231], v[244:245]
	v_pk_mul_f32 v[238:239], v[148:149], v[244:245]
	v_pk_fma_f32 v[48:49], v[122:123], v[232:233], v[246:247]
	v_pk_mul_f32 v[242:243], v[150:151], v[246:247]
	v_pk_fma_f32 v[38:39], v[124:125], v[234:235], v[248:249]
	v_pk_fma_f32 v[238:239], v[152:153], v[248:249], v[238:239]
	v_pk_fma_f32 v[32:33], v[126:127], v[236:237], v[250:251]
	v_pk_fma_f32 v[242:243], v[154:155], v[250:251], v[242:243]
	ds_read_b128 v[120:123], v188 offset:22528
	ds_read_b128 v[124:127], v188 offset:22784
	ds_read_b128 v[148:151], v188 offset:5632
	ds_read_b128 v[152:155], v188 offset:5888
	s_waitcnt lgkmcnt(8)
	v_pk_add_f32 v[230:231], v[182:183], v[36:37] op_sel_hi:[0,1] neg_lo:[0,1] neg_hi:[0,1]
	v_pk_add_f32 v[232:233], v[182:183], v[48:49] op_sel_hi:[0,1] neg_lo:[0,1] neg_hi:[0,1]
	v_pk_add_f32 v[234:235], v[182:183], v[38:39] op_sel_hi:[0,1] neg_lo:[0,1] neg_hi:[0,1]
	v_pk_add_f32 v[236:237], v[182:183], v[32:33] op_sel_hi:[0,1] neg_lo:[0,1] neg_hi:[0,1]
	v_pk_add_f32 v[238:239], v[238:239], v[242:243]
	v_add_f32_e32 v222, v238, v239
	v_pk_fma_f32 v[244:245], v[136:137], v[230:231], v[36:37]
	v_pk_mul_f32 v[240:241], v[112:113], v[36:37]
	v_pk_fma_f32 v[246:247], v[138:139], v[232:233], v[48:49]
	v_pk_mul_f32 v[196:197], v[114:115], v[48:49]
	v_pk_fma_f32 v[248:249], v[144:145], v[234:235], v[38:39]
	v_pk_fma_f32 v[240:241], v[116:117], v[38:39], v[240:241]
	v_pk_fma_f32 v[250:251], v[146:147], v[236:237], v[32:33]
	v_pk_fma_f32 v[196:197], v[118:119], v[32:33], v[196:197]
	ds_read_b128 v[136:139], v188 offset:23040
	ds_read_b128 v[144:147], v188 offset:23296
	ds_read_b128 v[112:115], v188 offset:6144
	ds_read_b128 v[116:119], v188 offset:6400
	s_waitcnt lgkmcnt(8)
	v_pk_add_f32 v[230:231], v[182:183], v[244:245] op_sel:[1,0] op_sel_hi:[1,1] neg_lo:[0,1] neg_hi:[0,1]
	v_pk_add_f32 v[232:233], v[182:183], v[246:247] op_sel:[1,0] op_sel_hi:[1,1] neg_lo:[0,1] neg_hi:[0,1]
	v_pk_add_f32 v[234:235], v[182:183], v[248:249] op_sel:[1,0] op_sel_hi:[1,1] neg_lo:[0,1] neg_hi:[0,1]
	v_pk_add_f32 v[236:237], v[182:183], v[250:251] op_sel:[1,0] op_sel_hi:[1,1] neg_lo:[0,1] neg_hi:[0,1]
	v_pk_add_f32 v[240:241], v[240:241], v[196:197]
	v_add_f32_e32 v223, v240, v241
	v_pk_fma_f32 v[36:37], v[156:157], v[230:231], v[244:245]
	v_pk_mul_f32 v[238:239], v[128:129], v[244:245]
	v_pk_fma_f32 v[48:49], v[158:159], v[232:233], v[246:247]
	v_pk_mul_f32 v[242:243], v[130:131], v[246:247]
	v_pk_fma_f32 v[38:39], v[168:169], v[234:235], v[248:249]
	v_pk_fma_f32 v[238:239], v[132:133], v[248:249], v[238:239]
	v_pk_fma_f32 v[32:33], v[170:171], v[236:237], v[250:251]
	v_pk_fma_f32 v[242:243], v[134:135], v[250:251], v[242:243]
	ds_read_b128 v[156:159], v188 offset:23552
	ds_read_b128 v[168:171], v188 offset:23808
	ds_read_b128 v[128:131], v188 offset:6656
	ds_read_b128 v[132:135], v188 offset:6912
	s_waitcnt lgkmcnt(8)
	v_pk_add_f32 v[230:231], v[184:185], v[36:37] op_sel_hi:[0,1] neg_lo:[0,1] neg_hi:[0,1]
	v_pk_add_f32 v[232:233], v[184:185], v[48:49] op_sel_hi:[0,1] neg_lo:[0,1] neg_hi:[0,1]
	v_pk_add_f32 v[234:235], v[184:185], v[38:39] op_sel_hi:[0,1] neg_lo:[0,1] neg_hi:[0,1]
	v_pk_add_f32 v[236:237], v[184:185], v[32:33] op_sel_hi:[0,1] neg_lo:[0,1] neg_hi:[0,1]
	v_pk_add_f32 v[238:239], v[238:239], v[242:243]
	v_add_f32_e32 v224, v238, v239
	v_pk_fma_f32 v[244:245], v[120:121], v[230:231], v[36:37]
	v_pk_mul_f32 v[240:241], v[148:149], v[36:37]
	v_pk_fma_f32 v[246:247], v[122:123], v[232:233], v[48:49]
	v_pk_mul_f32 v[196:197], v[150:151], v[48:49]
	v_pk_fma_f32 v[248:249], v[124:125], v[234:235], v[38:39]
	v_pk_fma_f32 v[240:241], v[152:153], v[38:39], v[240:241]
	v_pk_fma_f32 v[250:251], v[126:127], v[236:237], v[32:33]
	v_pk_fma_f32 v[196:197], v[154:155], v[32:33], v[196:197]
	ds_read_b128 v[120:123], v188 offset:24064
	ds_read_b128 v[124:127], v188 offset:24320
	ds_read_b128 v[148:151], v188 offset:7168
	ds_read_b128 v[152:155], v188 offset:7424
	s_waitcnt lgkmcnt(8)
	v_pk_add_f32 v[230:231], v[184:185], v[244:245] op_sel:[1,0] op_sel_hi:[1,1] neg_lo:[0,1] neg_hi:[0,1]
	v_pk_add_f32 v[232:233], v[184:185], v[246:247] op_sel:[1,0] op_sel_hi:[1,1] neg_lo:[0,1] neg_hi:[0,1]
	v_pk_add_f32 v[234:235], v[184:185], v[248:249] op_sel:[1,0] op_sel_hi:[1,1] neg_lo:[0,1] neg_hi:[0,1]
	v_pk_add_f32 v[236:237], v[184:185], v[250:251] op_sel:[1,0] op_sel_hi:[1,1] neg_lo:[0,1] neg_hi:[0,1]
	v_pk_add_f32 v[240:241], v[240:241], v[196:197]
	v_add_f32_e32 v225, v240, v241
	v_pk_fma_f32 v[36:37], v[136:137], v[230:231], v[244:245]
	v_pk_mul_f32 v[238:239], v[112:113], v[244:245]
	v_pk_fma_f32 v[48:49], v[138:139], v[232:233], v[246:247]
	v_pk_mul_f32 v[242:243], v[114:115], v[246:247]
	v_pk_fma_f32 v[38:39], v[144:145], v[234:235], v[248:249]
	v_pk_fma_f32 v[238:239], v[116:117], v[248:249], v[238:239]
	v_pk_fma_f32 v[32:33], v[146:147], v[236:237], v[250:251]
	v_pk_fma_f32 v[242:243], v[118:119], v[250:251], v[242:243]
	ds_read_b128 v[112:115], v188 offset:7680
	ds_read_b128 v[116:119], v188 offset:7936
	s_waitcnt lgkmcnt(6)
; DI float dpp_row_sum16(float v) {
;   v += __int_as_float(__builtin_amdgcn_update_dpp(0, __float_as_int(v), 0xB1, 0xF, 0xF, true));
;   v += __int_as_float(__builtin_amdgcn_update_dpp(0, __float_as_int(v), 0x4E, 0xF, 0xF, true));
;   v += __int_as_float(__builtin_amdgcn_update_dpp(0, __float_as_int(v), 0x141, 0xF, 0xF, true));
;   v += __int_as_float(__builtin_amdgcn_update_dpp(0, __float_as_int(v), 0x140, 0xF, 0xF, true));
;   return v;
; }
	v_pk_add_f32 v[230:231], v[186:187], v[36:37] op_sel_hi:[0,1] neg_lo:[0,1] neg_hi:[0,1]
	v_pk_add_f32 v[232:233], v[186:187], v[48:49] op_sel_hi:[0,1] neg_lo:[0,1] neg_hi:[0,1]
	v_pk_add_f32 v[234:235], v[186:187], v[38:39] op_sel_hi:[0,1] neg_lo:[0,1] neg_hi:[0,1]
	v_pk_add_f32 v[236:237], v[186:187], v[32:33] op_sel_hi:[0,1] neg_lo:[0,1] neg_hi:[0,1]
	v_pk_add_f32 v[238:239], v[238:239], v[242:243]
	v_add_f32_e32 v226, v238, v239
	v_pk_fma_f32 v[244:245], v[156:157], v[230:231], v[36:37]
	v_pk_mul_f32 v[240:241], v[128:129], v[36:37]
	v_pk_fma_f32 v[246:247], v[158:159], v[232:233], v[48:49]
	v_pk_mul_f32 v[196:197], v[130:131], v[48:49]
	v_pk_fma_f32 v[248:249], v[168:169], v[234:235], v[38:39]
	v_pk_fma_f32 v[240:241], v[132:133], v[38:39], v[240:241]
	v_pk_fma_f32 v[250:251], v[170:171], v[236:237], v[32:33]
	v_pk_fma_f32 v[196:197], v[134:135], v[32:33], v[196:197]
	s_waitcnt lgkmcnt(2)
	v_pk_add_f32 v[230:231], v[186:187], v[244:245] op_sel:[1,0] op_sel_hi:[1,1] neg_lo:[0,1] neg_hi:[0,1]
	v_pk_add_f32 v[232:233], v[186:187], v[246:247] op_sel:[1,0] op_sel_hi:[1,1] neg_lo:[0,1] neg_hi:[0,1]
	v_pk_add_f32 v[234:235], v[186:187], v[248:249] op_sel:[1,0] op_sel_hi:[1,1] neg_lo:[0,1] neg_hi:[0,1]
	v_pk_add_f32 v[236:237], v[186:187], v[250:251] op_sel:[1,0] op_sel_hi:[1,1] neg_lo:[0,1] neg_hi:[0,1]
	v_pk_add_f32 v[240:241], v[240:241], v[196:197]
	v_add_f32_e32 v227, v240, v241
	v_pk_fma_f32 v[36:37], v[120:121], v[230:231], v[244:245]
	v_pk_mul_f32 v[238:239], v[148:149], v[244:245]
	v_pk_fma_f32 v[48:49], v[122:123], v[232:233], v[246:247]
	v_pk_mul_f32 v[242:243], v[150:151], v[246:247]
	v_pk_fma_f32 v[38:39], v[124:125], v[234:235], v[248:249]
	v_pk_fma_f32 v[238:239], v[152:153], v[248:249], v[238:239]
	v_pk_fma_f32 v[32:33], v[126:127], v[236:237], v[250:251]
	v_pk_fma_f32 v[242:243], v[154:155], v[250:251], v[242:243]
	s_waitcnt lgkmcnt(0)
	v_pk_add_f32 v[238:239], v[238:239], v[242:243]
	v_add_f32_e32 v228, v238, v239
	v_pk_mul_f32 v[240:241], v[112:113], v[36:37]
	v_add_f32_dpp v214, v214, v214 row_mirror row_mask:0xf bank_mask:0x3 bound_ctrl:1
	v_pk_mul_f32 v[196:197], v[114:115], v[48:49]
	v_add_f32_dpp v214, v222, v222 row_mirror row_mask:0xf bank_mask:0xc bound_ctrl:1
	v_pk_fma_f32 v[240:241], v[116:117], v[38:39], v[240:241]
	v_add_f32_dpp v215, v215, v215 row_mirror row_mask:0xf bank_mask:0x3 bound_ctrl:1
	v_pk_fma_f32 v[196:197], v[118:119], v[32:33], v[196:197]
	v_add_f32_dpp v215, v223, v223 row_mirror row_mask:0xf bank_mask:0xc bound_ctrl:1
	v_pk_add_f32 v[240:241], v[240:241], v[196:197]
	v_add_f32_e32 v229, v240, v241
	v_add_f32_dpp v216, v216, v216 row_mirror row_mask:0xf bank_mask:0x3 bound_ctrl:1
	v_add_f32_dpp v216, v224, v224 row_mirror row_mask:0xf bank_mask:0xc bound_ctrl:1
	v_add_f32_dpp v217, v217, v217 row_mirror row_mask:0xf bank_mask:0x3 bound_ctrl:1
	v_add_f32_dpp v217, v225, v225 row_mirror row_mask:0xf bank_mask:0xc bound_ctrl:1
	v_add_f32_dpp v218, v218, v218 row_mirror row_mask:0xf bank_mask:0x3 bound_ctrl:1
	v_add_f32_dpp v218, v226, v226 row_mirror row_mask:0xf bank_mask:0xc bound_ctrl:1
	v_add_f32_dpp v219, v219, v219 row_mirror row_mask:0xf bank_mask:0x3 bound_ctrl:1
	v_add_f32_dpp v219, v227, v227 row_mirror row_mask:0xf bank_mask:0xc bound_ctrl:1
	v_add_f32_dpp v220, v220, v220 row_mirror row_mask:0xf bank_mask:0x3 bound_ctrl:1
	v_add_f32_dpp v220, v228, v228 row_mirror row_mask:0xf bank_mask:0xc bound_ctrl:1
	v_add_f32_dpp v221, v221, v221 row_mirror row_mask:0xf bank_mask:0x3 bound_ctrl:1
	v_add_f32_dpp v221, v229, v229 row_mirror row_mask:0xf bank_mask:0xc bound_ctrl:1
	v_add_f32_dpp v214, v214, v214 row_half_mirror row_mask:0xf bank_mask:0x5 bound_ctrl:1
	v_add_f32_dpp v214, v218, v218 row_half_mirror row_mask:0xf bank_mask:0xa bound_ctrl:1
	v_add_f32_dpp v215, v215, v215 row_half_mirror row_mask:0xf bank_mask:0x5 bound_ctrl:1
	v_add_f32_dpp v215, v219, v219 row_half_mirror row_mask:0xf bank_mask:0xa bound_ctrl:1
	v_add_f32_dpp v216, v216, v216 row_half_mirror row_mask:0xf bank_mask:0x5 bound_ctrl:1
	v_add_f32_dpp v216, v220, v220 row_half_mirror row_mask:0xf bank_mask:0xa bound_ctrl:1
	v_add_f32_dpp v217, v217, v217 row_half_mirror row_mask:0xf bank_mask:0x5 bound_ctrl:1
	v_add_f32_dpp v217, v221, v221 row_half_mirror row_mask:0xf bank_mask:0xa bound_ctrl:1
	v_add_f32_dpp v192, v214, v214 quad_perm:[2,3,0,1] row_mask:0xf bank_mask:0xf bound_ctrl:1
	v_add_f32_dpp v193, v216, v216 quad_perm:[2,3,0,1] row_mask:0xf bank_mask:0xf bound_ctrl:1
	v_add_f32_dpp v194, v215, v215 quad_perm:[2,3,0,1] row_mask:0xf bank_mask:0xf bound_ctrl:1
	v_add_f32_dpp v195, v217, v217 quad_perm:[2,3,0,1] row_mask:0xf bank_mask:0xf bound_ctrl:1
	v_cndmask_b32_e64 v214, v193, v192, s[42:43]
	v_cndmask_b32_e64 v215, v195, v194, s[42:43]
	s_nop 0
	v_add_f32_dpp v192, v214, v214 quad_perm:[1,0,3,2] row_mask:0xf bank_mask:0xf bound_ctrl:1
	v_add_f32_dpp v193, v215, v215 quad_perm:[1,0,3,2] row_mask:0xf bank_mask:0xf bound_ctrl:1
	v_or_b32_e32 v24, s25, v26
	s_and_b64 vcc, exec, s[0:1]
	v_cndmask_b32_e64 v25, v193, v192, s[44:45]
	s_cbranch_vccz .LBB0_218
	s_mov_b64 s[36:37], -1
	s_and_b64 vcc, exec, s[76:77]
	s_cbranch_vccz .LBB0_222
	v_sub_u32_e32 v91, 0x21ff, v24
	s_mov_b64 s[36:37], 0

.LBB0_243:
	v_lshl_add_u32 v188, s30, 9, v69
	v_lshl_add_u32 v189, s30, 7, v72
	v_add_u32_e32 v190, 0x11400, v189
	v_add_u32_e32 v189, 0x11000, v189
	ds_read2_b32 v[172:173], v189 offset1:32
	ds_read2_b32 v[174:175], v189 offset0:64 offset1:96
	ds_read2_b32 v[176:177], v189 offset0:128 offset1:160
	ds_read2_b32 v[178:179], v189 offset0:192 offset1:224
	ds_read_b128 v[120:123], v188 offset:53248
	ds_read_b128 v[124:127], v188 offset:53504
	ds_read_b128 v[112:115], v188 offset:36864
	ds_read_b128 v[116:119], v188 offset:37120
	ds_read_b128 v[136:139], v188 offset:53760
	ds_read_b128 v[144:147], v188 offset:54016
	ds_read_b128 v[156:159], v188 offset:54272
	ds_read_b128 v[168:171], v188 offset:54528
	ds_read_b128 v[128:131], v188 offset:37376
	ds_read_b128 v[132:135], v188 offset:37632
	s_waitcnt lgkmcnt(8)
	v_pk_add_f32 v[230:231], v[172:173], v[36:37] op_sel_hi:[0,1] neg_lo:[0,1] neg_hi:[0,1]
	v_pk_add_f32 v[232:233], v[172:173], v[48:49] op_sel_hi:[0,1] neg_lo:[0,1] neg_hi:[0,1]
	v_pk_add_f32 v[234:235], v[172:173], v[38:39] op_sel_hi:[0,1] neg_lo:[0,1] neg_hi:[0,1]
	v_pk_add_f32 v[236:237], v[172:173], v[32:33] op_sel_hi:[0,1] neg_lo:[0,1] neg_hi:[0,1]
	v_pk_fma_f32 v[244:245], v[120:121], v[230:231], v[36:37]
	v_pk_fma_f32 v[246:247], v[122:123], v[232:233], v[48:49]
	v_pk_fma_f32 v[248:249], v[124:125], v[234:235], v[38:39]
	v_pk_fma_f32 v[250:251], v[126:127], v[236:237], v[32:33]
	ds_read_b128 v[120:123], v188 offset:54784
	ds_read_b128 v[124:127], v188 offset:55040
	ds_read_b128 v[148:151], v188 offset:37888
	ds_read_b128 v[152:155], v188 offset:38144
	s_waitcnt lgkmcnt(8)
	v_pk_add_f32 v[230:231], v[172:173], v[244:245] op_sel:[1,0] op_sel_hi:[1,1] neg_lo:[0,1] neg_hi:[0,1]
	v_pk_add_f32 v[232:233], v[172:173], v[246:247] op_sel:[1,0] op_sel_hi:[1,1] neg_lo:[0,1] neg_hi:[0,1]
	v_pk_add_f32 v[234:235], v[172:173], v[248:249] op_sel:[1,0] op_sel_hi:[1,1] neg_lo:[0,1] neg_hi:[0,1]
	v_pk_add_f32 v[236:237], v[172:173], v[250:251] op_sel:[1,0] op_sel_hi:[1,1] neg_lo:[0,1] neg_hi:[0,1]
	v_pk_fma_f32 v[36:37], v[136:137], v[230:231], v[244:245]
	v_pk_mul_f32 v[238:239], v[112:113], v[244:245]
	v_pk_fma_f32 v[48:49], v[138:139], v[232:233], v[246:247]
	v_pk_mul_f32 v[242:243], v[114:115], v[246:247]
	v_pk_fma_f32 v[38:39], v[144:145], v[234:235], v[248:249]
	v_pk_fma_f32 v[238:239], v[116:117], v[248:249], v[238:239]
	v_pk_fma_f32 v[32:33], v[146:147], v[236:237], v[250:251]
	v_pk_fma_f32 v[242:243], v[118:119], v[250:251], v[242:243]
	ds_read_b128 v[136:139], v188 offset:55296
	ds_read_b128 v[144:147], v188 offset:55552
	ds_read_b128 v[112:115], v188 offset:38400
	ds_read_b128 v[116:119], v188 offset:38656
	s_waitcnt lgkmcnt(8)
	v_pk_add_f32 v[230:231], v[174:175], v[36:37] op_sel_hi:[0,1] neg_lo:[0,1] neg_hi:[0,1]
	v_pk_add_f32 v[232:233], v[174:175], v[48:49] op_sel_hi:[0,1] neg_lo:[0,1] neg_hi:[0,1]
	v_pk_add_f32 v[234:235], v[174:175], v[38:39] op_sel_hi:[0,1] neg_lo:[0,1] neg_hi:[0,1]
	v_pk_add_f32 v[236:237], v[174:175], v[32:33] op_sel_hi:[0,1] neg_lo:[0,1] neg_hi:[0,1]
	v_pk_add_f32 v[238:239], v[238:239], v[242:243]
	v_add_f32_e32 v214, v238, v239
	v_pk_fma_f32 v[244:245], v[156:157], v[230:231], v[36:37]
	v_pk_mul_f32 v[240:241], v[128:129], v[36:37]
	v_pk_fma_f32 v[246:247], v[158:159], v[232:233], v[48:49]
	v_pk_mul_f32 v[196:197], v[130:131], v[48:49]
	v_pk_fma_f32 v[248:249], v[168:169], v[234:235], v[38:39]
	v_pk_fma_f32 v[240:241], v[132:133], v[38:39], v[240:241]
	v_pk_fma_f32 v[250:251], v[170:171], v[236:237], v[32:33]
	v_pk_fma_f32 v[196:197], v[134:135], v[32:33], v[196:197]
	ds_read_b128 v[156:159], v188 offset:55808
	ds_read_b128 v[168:171], v188 offset:56064
	ds_read_b128 v[128:131], v188 offset:38912
	ds_read_b128 v[132:135], v188 offset:39168
	s_waitcnt lgkmcnt(8)
	v_pk_add_f32 v[230:231], v[174:175], v[244:245] op_sel:[1,0] op_sel_hi:[1,1] neg_lo:[0,1] neg_hi:[0,1]
	v_pk_add_f32 v[232:233], v[174:175], v[246:247] op_sel:[1,0] op_sel_hi:[1,1] neg_lo:[0,1] neg_hi:[0,1]
	v_pk_add_f32 v[234:235], v[174:175], v[248:249] op_sel:[1,0] op_sel_hi:[1,1] neg_lo:[0,1] neg_hi:[0,1]
	v_pk_add_f32 v[236:237], v[174:175], v[250:251] op_sel:[1,0] op_sel_hi:[1,1] neg_lo:[0,1] neg_hi:[0,1]
	v_pk_add_f32 v[240:241], v[240:241], v[196:197]
	v_add_f32_e32 v215, v240, v241
	v_pk_fma_f32 v[36:37], v[120:121], v[230:231], v[244:245]
	v_pk_mul_f32 v[238:239], v[148:149], v[244:245]
	v_pk_fma_f32 v[48:49], v[122:123], v[232:233], v[246:247]
	v_pk_mul_f32 v[242:243], v[150:151], v[246:247]
	v_pk_fma_f32 v[38:39], v[124:125], v[234:235], v[248:249]
	v_pk_fma_f32 v[238:239], v[152:153], v[248:249], v[238:239]
	v_pk_fma_f32 v[32:33], v[126:127], v[236:237], v[250:251]
	v_pk_fma_f32 v[242:243], v[154:155], v[250:251], v[242:243]
	ds_read_b128 v[120:123], v188 offset:56320
	ds_read_b128 v[124:127], v188 offset:56576
	ds_read_b128 v[148:151], v188 offset:39424
	ds_read_b128 v[152:155], v188 offset:39680
	ds_read2_b32 v[180:181], v190 offset1:32
	ds_read2_b32 v[182:183], v190 offset0:64 offset1:96
	ds_read2_b32 v[184:185], v190 offset0:128 offset1:160
	ds_read2_b32 v[186:187], v190 offset0:192 offset1:224
	s_waitcnt lgkmcnt(12)
	v_pk_add_f32 v[230:231], v[176:177], v[36:37] op_sel_hi:[0,1] neg_lo:[0,1] neg_hi:[0,1]
	v_pk_add_f32 v[232:233], v[176:177], v[48:49] op_sel_hi:[0,1] neg_lo:[0,1] neg_hi:[0,1]
	v_pk_add_f32 v[234:235], v[176:177], v[38:39] op_sel_hi:[0,1] neg_lo:[0,1] neg_hi:[0,1]
	v_pk_add_f32 v[236:237], v[176:177], v[32:33] op_sel_hi:[0,1] neg_lo:[0,1] neg_hi:[0,1]
	v_pk_add_f32 v[238:239], v[238:239], v[242:243]
	v_add_f32_e32 v216, v238, v239
	v_pk_fma_f32 v[244:245], v[136:137], v[230:231], v[36:37]
	v_pk_mul_f32 v[240:241], v[112:113], v[36:37]
	v_pk_fma_f32 v[246:247], v[138:139], v[232:233], v[48:49]
	v_pk_mul_f32 v[196:197], v[114:115], v[48:49]
	v_pk_fma_f32 v[248:249], v[144:145], v[234:235], v[38:39]
	v_pk_fma_f32 v[240:241], v[116:117], v[38:39], v[240:241]
	v_pk_fma_f32 v[250:251], v[146:147], v[236:237], v[32:33]
	v_pk_fma_f32 v[196:197], v[118:119], v[32:33], v[196:197]
	ds_read_b128 v[136:139], v188 offset:56832
	ds_read_b128 v[144:147], v188 offset:57088
	ds_read_b128 v[112:115], v188 offset:39936
	ds_read_b128 v[116:119], v188 offset:40192
	s_waitcnt lgkmcnt(12)
	v_pk_add_f32 v[230:231], v[176:177], v[244:245] op_sel:[1,0] op_sel_hi:[1,1] neg_lo:[0,1] neg_hi:[0,1]
	v_pk_add_f32 v[232:233], v[176:177], v[246:247] op_sel:[1,0] op_sel_hi:[1,1] neg_lo:[0,1] neg_hi:[0,1]
	v_pk_add_f32 v[234:235], v[176:177], v[248:249] op_sel:[1,0] op_sel_hi:[1,1] neg_lo:[0,1] neg_hi:[0,1]
	v_pk_add_f32 v[236:237], v[176:177], v[250:251] op_sel:[1,0] op_sel_hi:[1,1] neg_lo:[0,1] neg_hi:[0,1]
	v_pk_add_f32 v[240:241], v[240:241], v[196:197]
	v_add_f32_e32 v217, v240, v241
	v_pk_fma_f32 v[36:37], v[156:157], v[230:231], v[244:245]
	v_pk_mul_f32 v[238:239], v[128:129], v[244:245]
	v_pk_fma_f32 v[48:49], v[158:159], v[232:233], v[246:247]
	v_pk_mul_f32 v[242:243], v[130:131], v[246:247]
	v_pk_fma_f32 v[38:39], v[168:169], v[234:235], v[248:249]
	v_pk_fma_f32 v[238:239], v[132:133], v[248:249], v[238:239]
	v_pk_fma_f32 v[32:33], v[170:171], v[236:237], v[250:251]
	v_pk_fma_f32 v[242:243], v[134:135], v[250:251], v[242:243]
	ds_read_b128 v[156:159], v188 offset:57344
	ds_read_b128 v[168:171], v188 offset:57600
	ds_read_b128 v[128:131], v188 offset:40448
	ds_read_b128 v[132:135], v188 offset:40704
	s_waitcnt lgkmcnt(12)
	v_pk_add_f32 v[230:231], v[178:179], v[36:37] op_sel_hi:[0,1] neg_lo:[0,1] neg_hi:[0,1]
	v_pk_add_f32 v[232:233], v[178:179], v[48:49] op_sel_hi:[0,1] neg_lo:[0,1] neg_hi:[0,1]
	v_pk_add_f32 v[234:235], v[178:179], v[38:39] op_sel_hi:[0,1] neg_lo:[0,1] neg_hi:[0,1]
	v_pk_add_f32 v[236:237], v[178:179], v[32:33] op_sel_hi:[0,1] neg_lo:[0,1] neg_hi:[0,1]
	v_pk_add_f32 v[238:239], v[238:239], v[242:243]
	v_add_f32_e32 v218, v238, v239
	v_pk_fma_f32 v[244:245], v[120:121], v[230:231], v[36:37]
	v_pk_mul_f32 v[240:241], v[148:149], v[36:37]
	v_pk_fma_f32 v[246:247], v[122:123], v[232:233], v[48:49]
	v_pk_mul_f32 v[196:197], v[150:151], v[48:49]
	v_pk_fma_f32 v[248:249], v[124:125], v[234:235], v[38:39]
	v_pk_fma_f32 v[240:241], v[152:153], v[38:39], v[240:241]
	v_pk_fma_f32 v[250:251], v[126:127], v[236:237], v[32:33]
	v_pk_fma_f32 v[196:197], v[154:155], v[32:33], v[196:197]
	ds_read_b128 v[120:123], v188 offset:57856
	ds_read_b128 v[124:127], v188 offset:58112
	ds_read_b128 v[148:151], v188 offset:40960
	ds_read_b128 v[152:155], v188 offset:41216
	s_waitcnt lgkmcnt(8)
	v_pk_add_f32 v[230:231], v[178:179], v[244:245] op_sel:[1,0] op_sel_hi:[1,1] neg_lo:[0,1] neg_hi:[0,1]
	v_pk_add_f32 v[232:233], v[178:179], v[246:247] op_sel:[1,0] op_sel_hi:[1,1] neg_lo:[0,1] neg_hi:[0,1]
	v_pk_add_f32 v[234:235], v[178:179], v[248:249] op_sel:[1,0] op_sel_hi:[1,1] neg_lo:[0,1] neg_hi:[0,1]
	v_pk_add_f32 v[236:237], v[178:179], v[250:251] op_sel:[1,0] op_sel_hi:[1,1] neg_lo:[0,1] neg_hi:[0,1]
	v_pk_add_f32 v[240:241], v[240:241], v[196:197]
	v_add_f32_e32 v219, v240, v241
	v_pk_fma_f32 v[36:37], v[136:137], v[230:231], v[244:245]
	v_pk_mul_f32 v[238:239], v[112:113], v[244:245]
	v_pk_fma_f32 v[48:49], v[138:139], v[232:233], v[246:247]
	v_pk_mul_f32 v[242:243], v[114:115], v[246:247]
	v_pk_fma_f32 v[38:39], v[144:145], v[234:235], v[248:249]
	v_pk_fma_f32 v[238:239], v[116:117], v[248:249], v[238:239]
	v_pk_fma_f32 v[32:33], v[146:147], v[236:237], v[250:251]
	v_pk_fma_f32 v[242:243], v[118:119], v[250:251], v[242:243]
	ds_read_b128 v[136:139], v188 offset:58368
	ds_read_b128 v[144:147], v188 offset:58624
	ds_read_b128 v[112:115], v188 offset:41472
	ds_read_b128 v[116:119], v188 offset:41728
	s_waitcnt lgkmcnt(8)
	v_pk_add_f32 v[230:231], v[180:181], v[36:37] op_sel_hi:[0,1] neg_lo:[0,1] neg_hi:[0,1]
	v_pk_add_f32 v[232:233], v[180:181], v[48:49] op_sel_hi:[0,1] neg_lo:[0,1] neg_hi:[0,1]
	v_pk_add_f32 v[234:235], v[180:181], v[38:39] op_sel_hi:[0,1] neg_lo:[0,1] neg_hi:[0,1]
	v_pk_add_f32 v[236:237], v[180:181], v[32:33] op_sel_hi:[0,1] neg_lo:[0,1] neg_hi:[0,1]
	v_pk_add_f32 v[238:239], v[238:239], v[242:243]
	v_add_f32_e32 v220, v238, v239
	v_pk_fma_f32 v[244:245], v[156:157], v[230:231], v[36:37]
	v_pk_mul_f32 v[240:241], v[128:129], v[36:37]
	v_pk_fma_f32 v[246:247], v[158:159], v[232:233], v[48:49]
	v_pk_mul_f32 v[196:197], v[130:131], v[48:49]
	v_pk_fma_f32 v[248:249], v[168:169], v[234:235], v[38:39]
	v_pk_fma_f32 v[240:241], v[132:133], v[38:39], v[240:241]
	v_pk_fma_f32 v[250:251], v[170:171], v[236:237], v[32:33]
	v_pk_fma_f32 v[196:197], v[134:135], v[32:33], v[196:197]
	ds_read_b128 v[156:159], v188 offset:58880
	ds_read_b128 v[168:171], v188 offset:59136
	ds_read_b128 v[128:131], v188 offset:41984
	ds_read_b128 v[132:135], v188 offset:42240
	s_waitcnt lgkmcnt(8)
	v_pk_add_f32 v[230:231], v[180:181], v[244:245] op_sel:[1,0] op_sel_hi:[1,1] neg_lo:[0,1] neg_hi:[0,1]
	v_pk_add_f32 v[232:233], v[180:181], v[246:247] op_sel:[1,0] op_sel_hi:[1,1] neg_lo:[0,1] neg_hi:[0,1]
	v_pk_add_f32 v[234:235], v[180:181], v[248:249] op_sel:[1,0] op_sel_hi:[1,1] neg_lo:[0,1] neg_hi:[0,1]
	v_pk_add_f32 v[236:237], v[180:181], v[250:251] op_sel:[1,0] op_sel_hi:[1,1] neg_lo:[0,1] neg_hi:[0,1]
	v_pk_add_f32 v[240:241], v[240:241], v[196:197]
	v_add_f32_e32 v221, v240, v241
	v_pk_fma_f32 v[36:37], v[120:121], v[230:231], v[244:245]
	v_pk_mul_f32 v[238:239], v[148:149], v[244:245]
	v_pk_fma_f32 v[48:49], v[122:123], v[232:233], v[246:247]
	v_pk_mul_f32 v[242:243], v[150:151], v[246:247]
	v_pk_fma_f32 v[38:39], v[124:125], v[234:235], v[248:249]
	v_pk_fma_f32 v[238:239], v[152:153], v[248:249], v[238:239]
	v_pk_fma_f32 v[32:33], v[126:127], v[236:237], v[250:251]
	v_pk_fma_f32 v[242:243], v[154:155], v[250:251], v[242:243]
	ds_read_b128 v[120:123], v188 offset:59392
	ds_read_b128 v[124:127], v188 offset:59648
	ds_read_b128 v[148:151], v188 offset:42496
	ds_read_b128 v[152:155], v188 offset:42752
	s_waitcnt lgkmcnt(8)
	v_pk_add_f32 v[230:231], v[182:183], v[36:37] op_sel_hi:[0,1] neg_lo:[0,1] neg_hi:[0,1]
	v_pk_add_f32 v[232:233], v[182:183], v[48:49] op_sel_hi:[0,1] neg_lo:[0,1] neg_hi:[0,1]
	v_pk_add_f32 v[234:235], v[182:183], v[38:39] op_sel_hi:[0,1] neg_lo:[0,1] neg_hi:[0,1]
	v_pk_add_f32 v[236:237], v[182:183], v[32:33] op_sel_hi:[0,1] neg_lo:[0,1] neg_hi:[0,1]
	v_pk_add_f32 v[238:239], v[238:239], v[242:243]
	v_add_f32_e32 v222, v238, v239
	v_pk_fma_f32 v[244:245], v[136:137], v[230:231], v[36:37]
	v_pk_mul_f32 v[240:241], v[112:113], v[36:37]
	v_pk_fma_f32 v[246:247], v[138:139], v[232:233], v[48:49]
	v_pk_mul_f32 v[196:197], v[114:115], v[48:49]
	v_pk_fma_f32 v[248:249], v[144:145], v[234:235], v[38:39]
	v_pk_fma_f32 v[240:241], v[116:117], v[38:39], v[240:241]
	v_pk_fma_f32 v[250:251], v[146:147], v[236:237], v[32:33]
	v_pk_fma_f32 v[196:197], v[118:119], v[32:33], v[196:197]
	ds_read_b128 v[136:139], v188 offset:59904
	ds_read_b128 v[144:147], v188 offset:60160
	ds_read_b128 v[112:115], v188 offset:43008
	ds_read_b128 v[116:119], v188 offset:43264
	s_waitcnt lgkmcnt(8)
	v_pk_add_f32 v[230:231], v[182:183], v[244:245] op_sel:[1,0] op_sel_hi:[1,1] neg_lo:[0,1] neg_hi:[0,1]
	v_pk_add_f32 v[232:233], v[182:183], v[246:247] op_sel:[1,0] op_sel_hi:[1,1] neg_lo:[0,1] neg_hi:[0,1]
	v_pk_add_f32 v[234:235], v[182:183], v[248:249] op_sel:[1,0] op_sel_hi:[1,1] neg_lo:[0,1] neg_hi:[0,1]
	v_pk_add_f32 v[236:237], v[182:183], v[250:251] op_sel:[1,0] op_sel_hi:[1,1] neg_lo:[0,1] neg_hi:[0,1]
	v_pk_add_f32 v[240:241], v[240:241], v[196:197]
	v_add_f32_e32 v223, v240, v241
	v_pk_fma_f32 v[36:37], v[156:157], v[230:231], v[244:245]
	v_pk_mul_f32 v[238:239], v[128:129], v[244:245]
	v_pk_fma_f32 v[48:49], v[158:159], v[232:233], v[246:247]
	v_pk_mul_f32 v[242:243], v[130:131], v[246:247]
	v_pk_fma_f32 v[38:39], v[168:169], v[234:235], v[248:249]
	v_pk_fma_f32 v[238:239], v[132:133], v[248:249], v[238:239]
	v_pk_fma_f32 v[32:33], v[170:171], v[236:237], v[250:251]
	v_pk_fma_f32 v[242:243], v[134:135], v[250:251], v[242:243]
	ds_read_b128 v[156:159], v188 offset:60416
	ds_read_b128 v[168:171], v188 offset:60672
	ds_read_b128 v[128:131], v188 offset:43520
	ds_read_b128 v[132:135], v188 offset:43776
	s_waitcnt lgkmcnt(8)
	v_pk_add_f32 v[230:231], v[184:185], v[36:37] op_sel_hi:[0,1] neg_lo:[0,1] neg_hi:[0,1]
	v_pk_add_f32 v[232:233], v[184:185], v[48:49] op_sel_hi:[0,1] neg_lo:[0,1] neg_hi:[0,1]
	v_pk_add_f32 v[234:235], v[184:185], v[38:39] op_sel_hi:[0,1] neg_lo:[0,1] neg_hi:[0,1]
	v_pk_add_f32 v[236:237], v[184:185], v[32:33] op_sel_hi:[0,1] neg_lo:[0,1] neg_hi:[0,1]
	v_pk_add_f32 v[238:239], v[238:239], v[242:243]
	v_add_f32_e32 v224, v238, v239
	v_pk_fma_f32 v[244:245], v[120:121], v[230:231], v[36:37]
	v_pk_mul_f32 v[240:241], v[148:149], v[36:37]
	v_pk_fma_f32 v[246:247], v[122:123], v[232:233], v[48:49]
	v_pk_mul_f32 v[196:197], v[150:151], v[48:49]
	v_pk_fma_f32 v[248:249], v[124:125], v[234:235], v[38:39]
	v_pk_fma_f32 v[240:241], v[152:153], v[38:39], v[240:241]
	v_pk_fma_f32 v[250:251], v[126:127], v[236:237], v[32:33]
	v_pk_fma_f32 v[196:197], v[154:155], v[32:33], v[196:197]
	ds_read_b128 v[120:123], v188 offset:60928
	ds_read_b128 v[124:127], v188 offset:61184
	ds_read_b128 v[148:151], v188 offset:44032
	ds_read_b128 v[152:155], v188 offset:44288
	s_waitcnt lgkmcnt(8)
	v_pk_add_f32 v[230:231], v[184:185], v[244:245] op_sel:[1,0] op_sel_hi:[1,1] neg_lo:[0,1] neg_hi:[0,1]
	v_pk_add_f32 v[232:233], v[184:185], v[246:247] op_sel:[1,0] op_sel_hi:[1,1] neg_lo:[0,1] neg_hi:[0,1]
	v_pk_add_f32 v[234:235], v[184:185], v[248:249] op_sel:[1,0] op_sel_hi:[1,1] neg_lo:[0,1] neg_hi:[0,1]
	v_pk_add_f32 v[236:237], v[184:185], v[250:251] op_sel:[1,0] op_sel_hi:[1,1] neg_lo:[0,1] neg_hi:[0,1]
	v_pk_add_f32 v[240:241], v[240:241], v[196:197]
	v_add_f32_e32 v225, v240, v241
	v_pk_fma_f32 v[36:37], v[136:137], v[230:231], v[244:245]
	v_pk_mul_f32 v[238:239], v[112:113], v[244:245]
	v_pk_fma_f32 v[48:49], v[138:139], v[232:233], v[246:247]
	v_pk_mul_f32 v[242:243], v[114:115], v[246:247]
	v_pk_fma_f32 v[38:39], v[144:145], v[234:235], v[248:249]
	v_pk_fma_f32 v[238:239], v[116:117], v[248:249], v[238:239]
	v_pk_fma_f32 v[32:33], v[146:147], v[236:237], v[250:251]
	v_pk_fma_f32 v[242:243], v[118:119], v[250:251], v[242:243]
	ds_read_b128 v[112:115], v188 offset:44544
	ds_read_b128 v[116:119], v188 offset:44800
	s_waitcnt lgkmcnt(6)
; DI float dpp_row_sum16(float v) {
;   v += __int_as_float(__builtin_amdgcn_update_dpp(0, __float_as_int(v), 0xB1, 0xF, 0xF, true));
;   v += __int_as_float(__builtin_amdgcn_update_dpp(0, __float_as_int(v), 0x4E, 0xF, 0xF, true));
;   v += __int_as_float(__builtin_amdgcn_update_dpp(0, __float_as_int(v), 0x141, 0xF, 0xF, true));
;   v += __int_as_float(__builtin_amdgcn_update_dpp(0, __float_as_int(v), 0x140, 0xF, 0xF, true));
;   return v;
; }
	v_pk_add_f32 v[230:231], v[186:187], v[36:37] op_sel_hi:[0,1] neg_lo:[0,1] neg_hi:[0,1]
	v_pk_add_f32 v[232:233], v[186:187], v[48:49] op_sel_hi:[0,1] neg_lo:[0,1] neg_hi:[0,1]
	v_pk_add_f32 v[234:235], v[186:187], v[38:39] op_sel_hi:[0,1] neg_lo:[0,1] neg_hi:[0,1]
	v_pk_add_f32 v[236:237], v[186:187], v[32:33] op_sel_hi:[0,1] neg_lo:[0,1] neg_hi:[0,1]
	v_pk_add_f32 v[238:239], v[238:239], v[242:243]
	v_add_f32_e32 v226, v238, v239
	v_pk_fma_f32 v[244:245], v[156:157], v[230:231], v[36:37]
	v_pk_mul_f32 v[240:241], v[128:129], v[36:37]
	v_pk_fma_f32 v[246:247], v[158:159], v[232:233], v[48:49]
	v_pk_mul_f32 v[196:197], v[130:131], v[48:49]
	v_pk_fma_f32 v[248:249], v[168:169], v[234:235], v[38:39]
	v_pk_fma_f32 v[240:241], v[132:133], v[38:39], v[240:241]
	v_pk_fma_f32 v[250:251], v[170:171], v[236:237], v[32:33]
	v_pk_fma_f32 v[196:197], v[134:135], v[32:33], v[196:197]
	s_waitcnt lgkmcnt(2)
	v_pk_add_f32 v[230:231], v[186:187], v[244:245] op_sel:[1,0] op_sel_hi:[1,1] neg_lo:[0,1] neg_hi:[0,1]
	v_pk_add_f32 v[232:233], v[186:187], v[246:247] op_sel:[1,0] op_sel_hi:[1,1] neg_lo:[0,1] neg_hi:[0,1]
	v_pk_add_f32 v[234:235], v[186:187], v[248:249] op_sel:[1,0] op_sel_hi:[1,1] neg_lo:[0,1] neg_hi:[0,1]
	v_pk_add_f32 v[236:237], v[186:187], v[250:251] op_sel:[1,0] op_sel_hi:[1,1] neg_lo:[0,1] neg_hi:[0,1]
	v_pk_add_f32 v[240:241], v[240:241], v[196:197]
	v_add_f32_e32 v227, v240, v241
	v_pk_fma_f32 v[36:37], v[120:121], v[230:231], v[244:245]
	v_pk_mul_f32 v[238:239], v[148:149], v[244:245]
	v_pk_fma_f32 v[48:49], v[122:123], v[232:233], v[246:247]
	v_pk_mul_f32 v[242:243], v[150:151], v[246:247]
	v_pk_fma_f32 v[38:39], v[124:125], v[234:235], v[248:249]
	v_pk_fma_f32 v[238:239], v[152:153], v[248:249], v[238:239]
	v_pk_fma_f32 v[32:33], v[126:127], v[236:237], v[250:251]
	v_pk_fma_f32 v[242:243], v[154:155], v[250:251], v[242:243]
	s_waitcnt lgkmcnt(0)
	v_pk_add_f32 v[238:239], v[238:239], v[242:243]
	v_add_f32_e32 v228, v238, v239
	v_pk_mul_f32 v[240:241], v[112:113], v[36:37]
	v_add_f32_dpp v214, v214, v214 row_mirror row_mask:0xf bank_mask:0x3 bound_ctrl:1
	v_pk_mul_f32 v[196:197], v[114:115], v[48:49]
	v_add_f32_dpp v214, v222, v222 row_mirror row_mask:0xf bank_mask:0xc bound_ctrl:1
	v_pk_fma_f32 v[240:241], v[116:117], v[38:39], v[240:241]
	v_add_f32_dpp v215, v215, v215 row_mirror row_mask:0xf bank_mask:0x3 bound_ctrl:1
	v_pk_fma_f32 v[196:197], v[118:119], v[32:33], v[196:197]
	v_add_f32_dpp v215, v223, v223 row_mirror row_mask:0xf bank_mask:0xc bound_ctrl:1
	v_pk_add_f32 v[240:241], v[240:241], v[196:197]
	v_add_f32_e32 v229, v240, v241
	v_add_f32_dpp v216, v216, v216 row_mirror row_mask:0xf bank_mask:0x3 bound_ctrl:1
	v_add_f32_dpp v216, v224, v224 row_mirror row_mask:0xf bank_mask:0xc bound_ctrl:1
	v_add_f32_dpp v217, v217, v217 row_mirror row_mask:0xf bank_mask:0x3 bound_ctrl:1
	v_add_f32_dpp v217, v225, v225 row_mirror row_mask:0xf bank_mask:0xc bound_ctrl:1
	v_add_f32_dpp v218, v218, v218 row_mirror row_mask:0xf bank_mask:0x3 bound_ctrl:1
	v_add_f32_dpp v218, v226, v226 row_mirror row_mask:0xf bank_mask:0xc bound_ctrl:1
	v_add_f32_dpp v219, v219, v219 row_mirror row_mask:0xf bank_mask:0x3 bound_ctrl:1
	v_add_f32_dpp v219, v227, v227 row_mirror row_mask:0xf bank_mask:0xc bound_ctrl:1
	v_add_f32_dpp v220, v220, v220 row_mirror row_mask:0xf bank_mask:0x3 bound_ctrl:1
	v_add_f32_dpp v220, v228, v228 row_mirror row_mask:0xf bank_mask:0xc bound_ctrl:1
	v_add_f32_dpp v221, v221, v221 row_mirror row_mask:0xf bank_mask:0x3 bound_ctrl:1
	v_add_f32_dpp v221, v229, v229 row_mirror row_mask:0xf bank_mask:0xc bound_ctrl:1
	v_add_f32_dpp v214, v214, v214 row_half_mirror row_mask:0xf bank_mask:0x5 bound_ctrl:1
	v_add_f32_dpp v214, v218, v218 row_half_mirror row_mask:0xf bank_mask:0xa bound_ctrl:1
	v_add_f32_dpp v215, v215, v215 row_half_mirror row_mask:0xf bank_mask:0x5 bound_ctrl:1
	v_add_f32_dpp v215, v219, v219 row_half_mirror row_mask:0xf bank_mask:0xa bound_ctrl:1
	v_add_f32_dpp v216, v216, v216 row_half_mirror row_mask:0xf bank_mask:0x5 bound_ctrl:1
	v_add_f32_dpp v216, v220, v220 row_half_mirror row_mask:0xf bank_mask:0xa bound_ctrl:1
	v_add_f32_dpp v217, v217, v217 row_half_mirror row_mask:0xf bank_mask:0x5 bound_ctrl:1
	v_add_f32_dpp v217, v221, v221 row_half_mirror row_mask:0xf bank_mask:0xa bound_ctrl:1
	v_add_f32_dpp v192, v214, v214 quad_perm:[2,3,0,1] row_mask:0xf bank_mask:0xf bound_ctrl:1
	v_add_f32_dpp v193, v216, v216 quad_perm:[2,3,0,1] row_mask:0xf bank_mask:0xf bound_ctrl:1
	v_add_f32_dpp v194, v215, v215 quad_perm:[2,3,0,1] row_mask:0xf bank_mask:0xf bound_ctrl:1
	v_add_f32_dpp v195, v217, v217 quad_perm:[2,3,0,1] row_mask:0xf bank_mask:0xf bound_ctrl:1
	v_cndmask_b32_e64 v214, v193, v192, s[42:43]
	v_cndmask_b32_e64 v215, v195, v194, s[42:43]
	s_nop 0
	v_add_f32_dpp v192, v214, v214 quad_perm:[1,0,3,2] row_mask:0xf bank_mask:0xf bound_ctrl:1
	v_add_f32_dpp v193, v215, v215 quad_perm:[1,0,3,2] row_mask:0xf bank_mask:0xf bound_ctrl:1
	v_or_b32_e32 v24, s30, v74
	s_and_b64 vcc, exec, s[0:1]
	v_cndmask_b32_e64 v25, v193, v192, s[44:45]
	s_cbranch_vccz .LBB0_242
	s_mov_b64 s[30:31], -1
	s_and_b64 vcc, exec, s[76:77]
	s_cbranch_vccz .LBB0_246
	v_sub_u32_e32 v27, 0x21ff, v24
	s_mov_b64 s[30:31], 0
